# mlp1/mlp2 GEMM loops kept at priority 0 (attention partner wins), P0 pe@w1 loop loads de-serialised
# speedup vs baseline: 1.0712x; 1.0017x over previous
.LBB0_39:
	s_add_u32 s8, s2, s0
	s_addc_u32 s9, s3, s1
	global_load_dwordx4 v[6:9], v23, s[8:9] offset:48
	global_load_dwordx4 v[10:13], v23, s[8:9] offset:32
	global_load_dwordx4 v[24:27], v23, s[8:9] offset:16
	global_load_dwordx4 v[28:31], v23, s[8:9]
	v_add_co_u32_e32 v88, vcc, s68, v2
	s_movk_i32 s8, 0xe000
	s_nop 0
	v_addc_co_u32_e32 v89, vcc, -1, v3, vcc
	v_add_co_u32_e32 v90, vcc, s8, v2
	s_movk_i32 s8, 0xf000
	s_nop 0
	v_addc_co_u32_e32 v91, vcc, -1, v3, vcc
	v_add_co_u32_e32 v92, vcc, s8, v2
	s_nop 1
	v_addc_co_u32_e32 v93, vcc, -1, v3, vcc
	global_load_dword v72, v[88:89], off offset:-3072
	global_load_dword v73, v[88:89], off offset:-2048
	global_load_dword v74, v[88:89], off offset:-1024
	global_load_dword v75, v[90:91], off offset:-4096
	global_load_dword v76, v[90:91], off offset:-3072
	global_load_dword v77, v[90:91], off offset:-2048
	global_load_dword v78, v[90:91], off offset:-1024
	global_load_dword v79, v[90:91], off
	global_load_dword v80, v[92:93], off offset:-3072
	global_load_dword v81, v[92:93], off offset:-2048
	global_load_dword v82, v[92:93], off offset:-1024
	global_load_dword v83, v[2:3], off offset:-4096
	global_load_dword v84, v[2:3], off offset:-3072
	global_load_dword v85, v[2:3], off offset:-2048
	global_load_dword v86, v[2:3], off offset:-1024
	global_load_dword v87, v[2:3], off
	s_add_u32 s0, s0, 64
	s_addc_u32 s1, s1, 0
	s_mov_b64 s[8:9], 0x4000
	v_lshl_add_u64 v[2:3], v[2:3], 0, s[8:9]
	s_waitcnt vmcnt(15)
	v_fmac_f32_e32 v4, v28, v72
	s_waitcnt vmcnt(14)
	v_fmac_f32_e32 v4, v29, v73
	s_waitcnt vmcnt(13)
	v_fmac_f32_e32 v4, v30, v74
	s_waitcnt vmcnt(12)
	v_fmac_f32_e32 v4, v31, v75
	s_waitcnt vmcnt(11)
	v_fmac_f32_e32 v4, v24, v76
	s_waitcnt vmcnt(10)
	v_fmac_f32_e32 v4, v25, v77
	s_waitcnt vmcnt(9)
	v_fmac_f32_e32 v4, v26, v78
	s_waitcnt vmcnt(8)
	v_fmac_f32_e32 v4, v27, v79
	s_waitcnt vmcnt(7)
	v_fmac_f32_e32 v4, v10, v80
	s_waitcnt vmcnt(6)
	v_fmac_f32_e32 v4, v11, v81
	s_waitcnt vmcnt(5)
	v_fmac_f32_e32 v4, v12, v82
	s_waitcnt vmcnt(4)
	v_fmac_f32_e32 v4, v13, v83
	s_waitcnt vmcnt(3)
	v_fmac_f32_e32 v4, v6, v84
	s_waitcnt vmcnt(2)
	v_fmac_f32_e32 v4, v7, v85
	s_waitcnt vmcnt(1)
	v_fmac_f32_e32 v4, v8, v86
	s_waitcnt vmcnt(0)
	v_fmac_f32_e32 v4, v9, v87
	s_cmpk_eq_i32 s0, 0x200
	s_cbranch_scc0 .LBB0_39
	s_lshl_b32 s0, s95, 8
	s_add_i32 s46, s0, 0xffff4000
	s_mov_b64 s[0:1], 0xcd00000

.LBB0_665:
	s_setprio 0
	s_barrier
	s_waitcnt vmcnt(3)
	ds_write_b128 v182, v[166:169]
	s_waitcnt vmcnt(2)
	ds_write_b128 v182, v[162:165] offset:4608
	s_waitcnt vmcnt(1)
	ds_write_b128 v182, v[174:177] offset:9216
	s_waitcnt vmcnt(0)
	ds_write_b128 v182, v[170:173] offset:13824
	ds_write_b128 v182, v[130:133] offset:18432
	ds_write_b128 v182, v[134:137] offset:23040
	ds_write_b128 v182, v[138:141] offset:27648
	ds_write_b128 v182, v[142:145] offset:32256
	ds_write_b128 v182, v[146:149] offset:36864
	ds_write_b128 v182, v[150:153] offset:41472
	ds_write_b128 v182, v[154:157] offset:46080
	ds_write_b128 v182, v[158:161] offset:50688
	s_waitcnt lgkmcnt(0)
	s_setprio 0
	s_barrier
	s_setprio 0
	ds_read_b128 v[130:133], v0 offset:18432
	ds_read_b128 v[134:137], v194
	ds_read_b128 v[138:141], v194 offset:32
	ds_read_b128 v[142:145], v0 offset:18464
	ds_read_b128 v[146:149], v194 offset:4608
	ds_read_b128 v[150:153], v194 offset:4640
	s_waitcnt lgkmcnt(4)
	v_mfma_f32_32x32x16_bf16 v[114:129], v[130:133], v[134:137], v[114:129]
	s_waitcnt lgkmcnt(1)
	v_mfma_f32_32x32x16_bf16 v[82:97], v[130:133], v[146:149], v[82:97]
	ds_read_b128 v[130:133], v0 offset:23040
	ds_read_b128 v[154:157], v0 offset:23072
	s_waitcnt lgkmcnt(1)
	v_mfma_f32_32x32x16_bf16 v[98:113], v[130:133], v[134:137], v[98:113]
	v_mfma_f32_32x32x16_bf16 v[66:81], v[130:133], v[146:149], v[66:81]
	ds_read_b128 v[130:133], v0 offset:27648
	ds_read_b128 v[158:161], v0 offset:27680
	s_waitcnt lgkmcnt(1)
	v_mfma_f32_32x32x16_bf16 v[50:65], v[130:133], v[134:137], v[50:65]
	v_mfma_f32_32x32x16_bf16 v[18:33], v[130:133], v[146:149], v[18:33]
	ds_read_b128 v[130:133], v0 offset:32256
	ds_read_b128 v[162:165], v0 offset:32288
	s_waitcnt lgkmcnt(1)
	v_mfma_f32_32x32x16_bf16 v[34:49], v[130:133], v[134:137], v[34:49]
	v_mfma_f32_32x32x16_bf16 v[114:129], v[142:145], v[138:141], v[114:129]
	v_mfma_f32_32x32x16_bf16 v[82:97], v[142:145], v[150:153], v[82:97]
	v_mfma_f32_32x32x16_bf16 v[2:17], v[130:133], v[146:149], v[2:17]
	v_mfma_f32_32x32x16_bf16 v[98:113], v[154:157], v[138:141], v[98:113]
	v_mfma_f32_32x32x16_bf16 v[66:81], v[154:157], v[150:153], v[66:81]
	v_mfma_f32_32x32x16_bf16 v[50:65], v[158:161], v[138:141], v[50:65]
	v_mfma_f32_32x32x16_bf16 v[18:33], v[158:161], v[150:153], v[18:33]
	s_waitcnt lgkmcnt(0)
	v_mfma_f32_32x32x16_bf16 v[34:49], v[162:165], v[138:141], v[34:49]
	ds_read_b128 v[130:133], v0 offset:18496
	ds_read_b128 v[134:137], v194 offset:64
	ds_read_b128 v[158:161], v194 offset:96
	ds_read_b128 v[138:141], v0 offset:18528
	ds_read_b128 v[142:145], v194 offset:4672
	ds_read_b128 v[196:199], v194 offset:4704
	s_waitcnt lgkmcnt(4)
	v_mfma_f32_32x32x16_bf16 v[114:129], v[130:133], v[134:137], v[114:129]
	s_waitcnt lgkmcnt(1)
	v_mfma_f32_32x32x16_bf16 v[82:97], v[130:133], v[142:145], v[82:97]
	ds_read_b128 v[130:133], v0 offset:23104
	ds_read_b128 v[146:149], v0 offset:23136
	v_mfma_f32_32x32x16_bf16 v[2:17], v[162:165], v[150:153], v[2:17]
	s_waitcnt lgkmcnt(1)
	v_mfma_f32_32x32x16_bf16 v[98:113], v[130:133], v[134:137], v[98:113]
	v_mfma_f32_32x32x16_bf16 v[66:81], v[130:133], v[142:145], v[66:81]
	ds_read_b128 v[130:133], v0 offset:27712
	ds_read_b128 v[150:153], v0 offset:27744
	s_waitcnt lgkmcnt(1)
	v_mfma_f32_32x32x16_bf16 v[50:65], v[130:133], v[134:137], v[50:65]
	v_mfma_f32_32x32x16_bf16 v[18:33], v[130:133], v[142:145], v[18:33]
	ds_read_b128 v[130:133], v0 offset:32320
	ds_read_b128 v[200:203], v0 offset:32352
	s_waitcnt lgkmcnt(1)
	v_mfma_f32_32x32x16_bf16 v[34:49], v[130:133], v[134:137], v[34:49]
	v_lshl_add_u64 v[134:135], v[188:189], 0, s[18:19]
	v_lshl_add_u64 v[136:137], v[186:187], 0, s[18:19]
	v_mfma_f32_32x32x16_bf16 v[2:17], v[130:133], v[142:145], v[2:17]
	v_lshl_add_u64 v[130:131], v[192:193], 0, s[18:19]
	v_lshl_add_u64 v[142:143], v[184:185], 0, s[18:19]
	v_lshl_add_u64 v[132:133], v[190:191], 0, s[18:19]
	global_load_dwordx4 v[166:169], v[130:131], off
	global_load_dwordx4 v[162:165], v[132:133], off
	global_load_dwordx4 v[174:177], v[134:135], off
	global_load_dwordx4 v[170:173], v[136:137], off
	v_add_co_u32_e32 v130, vcc, s87, v142
	s_add_u32 s18, s18, 0x80
	s_nop 0
	v_addc_co_u32_e32 v131, vcc, 0, v143, vcc
	v_add_co_u32_e32 v134, vcc, s88, v142
	v_mfma_f32_32x32x16_bf16 v[114:129], v[138:141], v[158:161], v[114:129]
	s_nop 0
	v_addc_co_u32_e32 v135, vcc, 0, v143, vcc
	s_addc_u32 s19, s19, 0
	s_cmpk_lg_i32 s18, 0x380
	v_mfma_f32_32x32x16_bf16 v[82:97], v[138:141], v[196:199], v[82:97]
	v_add_co_u32_e32 v138, vcc, s89, v142
	s_nop 1
	v_addc_co_u32_e32 v139, vcc, 0, v143, vcc
	v_add_co_u32_e32 v144, vcc, s90, v142
	v_mfma_f32_32x32x16_bf16 v[98:113], v[146:149], v[158:161], v[98:113]
	s_nop 0
	v_addc_co_u32_e32 v145, vcc, 0, v143, vcc
	v_mfma_f32_32x32x16_bf16 v[66:81], v[146:149], v[196:199], v[66:81]
	v_add_co_u32_e32 v146, vcc, s91, v142
	s_nop 1
	v_addc_co_u32_e32 v147, vcc, 0, v143, vcc
	v_add_co_u32_e32 v154, vcc, s92, v142
	v_mfma_f32_32x32x16_bf16 v[50:65], v[150:153], v[158:161], v[50:65]
	s_nop 0
	v_addc_co_u32_e32 v155, vcc, 0, v143, vcc
	v_add_co_u32_e32 v156, vcc, s93, v142
	s_nop 1
	v_addc_co_u32_e32 v157, vcc, 0, v143, vcc
	v_add_co_u32_e32 v204, vcc, s94, v142
	v_mfma_f32_32x32x16_bf16 v[18:33], v[150:153], v[196:199], v[18:33]
	s_nop 0
	v_addc_co_u32_e32 v205, vcc, 0, v143, vcc
	global_load_dwordx4 v[130:133], v[130:131], off offset:128
	s_nop 0
	global_load_dwordx4 v[134:137], v[134:135], off offset:128
	s_nop 0
	global_load_dwordx4 v[138:141], v[138:139], off offset:128
	s_nop 0
	global_load_dwordx4 v[142:145], v[144:145], off offset:128
	s_nop 0
	global_load_dwordx4 v[146:149], v[146:147], off offset:128
	s_nop 0
	global_load_dwordx4 v[150:153], v[154:155], off offset:128
	s_nop 0
	global_load_dwordx4 v[154:157], v[156:157], off offset:128
	s_waitcnt lgkmcnt(0)
	v_mfma_f32_32x32x16_bf16 v[34:49], v[200:203], v[158:161], v[34:49]
	global_load_dwordx4 v[158:161], v[204:205], off offset:128
	v_mfma_f32_32x32x16_bf16 v[2:17], v[200:203], v[196:199], v[2:17]
	s_cbranch_scc1 .LBB0_665
	s_setprio 0
	s_barrier
	s_waitcnt vmcnt(11)
	ds_write_b128 v182, v[166:169]
	s_waitcnt vmcnt(10)
	ds_write_b128 v182, v[162:165] offset:4608
	s_waitcnt vmcnt(9)
	ds_write_b128 v182, v[174:177] offset:9216
	s_waitcnt vmcnt(8)
	ds_write_b128 v182, v[170:173] offset:13824
	s_waitcnt vmcnt(7)
	ds_write_b128 v182, v[130:133] offset:18432
	s_waitcnt vmcnt(6)
	ds_write_b128 v182, v[134:137] offset:23040
	s_waitcnt vmcnt(5)
	ds_write_b128 v182, v[138:141] offset:27648
	s_waitcnt vmcnt(4)
	ds_write_b128 v182, v[142:145] offset:32256
	s_waitcnt vmcnt(3)
	ds_write_b128 v182, v[146:149] offset:36864
	s_waitcnt vmcnt(2)
	ds_write_b128 v182, v[150:153] offset:41472
	s_waitcnt vmcnt(1)
	ds_write_b128 v182, v[154:157] offset:46080
	s_waitcnt vmcnt(0)
	ds_write_b128 v182, v[158:161] offset:50688
	s_waitcnt lgkmcnt(0)
	s_setprio 0
	s_barrier
	s_setprio 0
	ds_read_b128 v[130:133], v0 offset:18432
	ds_read_b128 v[134:137], v194
	ds_read_b128 v[138:141], v194 offset:32
	ds_read_b128 v[142:145], v0 offset:18464
	ds_read_b128 v[146:149], v194 offset:4608
	ds_read_b128 v[150:153], v194 offset:4640
	s_waitcnt lgkmcnt(4)
	v_mfma_f32_32x32x16_bf16 v[114:129], v[130:133], v[134:137], v[114:129]
	s_lshl_b32 s2, s4, 1
	s_add_i32 s2, s2, s5
	s_ashr_i32 s3, s2, 31
	s_lshl_b64 s[2:3], s[2:3], 21
	s_add_u32 s2, s34, s2
	s_addc_u32 s3, s35, s3
	s_add_u32 s2, s2, 0x8000000
	s_waitcnt lgkmcnt(1)
	v_mfma_f32_32x32x16_bf16 v[82:97], v[130:133], v[146:149], v[82:97]
	ds_read_b128 v[130:133], v0 offset:23040
	ds_read_b128 v[154:157], v0 offset:23072
	s_addc_u32 s3, s3, 0
	s_waitcnt lgkmcnt(1)
	v_mfma_f32_32x32x16_bf16 v[98:113], v[130:133], v[134:137], v[98:113]
	v_mfma_f32_32x32x16_bf16 v[66:81], v[130:133], v[146:149], v[66:81]
	ds_read_b128 v[130:133], v0 offset:27648
	ds_read_b128 v[158:161], v0 offset:27680
	s_waitcnt lgkmcnt(1)
	v_mfma_f32_32x32x16_bf16 v[50:65], v[130:133], v[134:137], v[50:65]
	v_mfma_f32_32x32x16_bf16 v[18:33], v[130:133], v[146:149], v[18:33]
	ds_read_b128 v[130:133], v0 offset:32256
	ds_read_b128 v[162:165], v0 offset:32288
	s_waitcnt lgkmcnt(1)
	v_mfma_f32_32x32x16_bf16 v[34:49], v[130:133], v[134:137], v[34:49]
	v_mfma_f32_32x32x16_bf16 v[2:17], v[130:133], v[146:149], v[2:17]
	v_mfma_f32_32x32x16_bf16 v[114:129], v[142:145], v[138:141], v[114:129]
	v_mfma_f32_32x32x16_bf16 v[82:97], v[142:145], v[150:153], v[82:97]
	v_mfma_f32_32x32x16_bf16 v[98:113], v[154:157], v[138:141], v[98:113]
	v_mfma_f32_32x32x16_bf16 v[66:81], v[154:157], v[150:153], v[66:81]
	v_mfma_f32_32x32x16_bf16 v[50:65], v[158:161], v[138:141], v[50:65]
	v_mfma_f32_32x32x16_bf16 v[18:33], v[158:161], v[150:153], v[18:33]
	s_waitcnt lgkmcnt(0)
	v_mfma_f32_32x32x16_bf16 v[34:49], v[162:165], v[138:141], v[34:49]
	ds_read_b128 v[130:133], v0 offset:18496
	ds_read_b128 v[134:137], v194 offset:64
	ds_read_b128 v[138:141], v194 offset:96
	ds_read_b128 v[142:145], v0 offset:18528
	v_mfma_f32_32x32x16_bf16 v[2:17], v[162:165], v[150:153], v[2:17]
	ds_read_b128 v[146:149], v194 offset:4672
	ds_read_b128 v[150:153], v194 offset:4704
	s_waitcnt lgkmcnt(4)
	v_mfma_f32_32x32x16_bf16 v[114:129], v[130:133], v[134:137], v[114:129]
	s_waitcnt lgkmcnt(1)
	v_mfma_f32_32x32x16_bf16 v[82:97], v[130:133], v[146:149], v[82:97]
	ds_read_b128 v[130:133], v0 offset:23104
	ds_read_b128 v[154:157], v0 offset:23136
	s_waitcnt lgkmcnt(1)
	v_mfma_f32_32x32x16_bf16 v[98:113], v[130:133], v[134:137], v[98:113]
	v_mfma_f32_32x32x16_bf16 v[66:81], v[130:133], v[146:149], v[66:81]
	ds_read_b128 v[130:133], v0 offset:27712
	ds_read_b128 v[158:161], v0 offset:27744
	s_waitcnt lgkmcnt(1)
	v_mfma_f32_32x32x16_bf16 v[50:65], v[130:133], v[134:137], v[50:65]
	v_mfma_f32_32x32x16_bf16 v[18:33], v[130:133], v[146:149], v[18:33]
	ds_read_b128 v[130:133], v0 offset:32320
	ds_read_b128 v[162:165], v0 offset:32352
	v_lshlrev_b32_e32 v0, 2, v181
	v_mov_b32_e32 v181, v1
	s_waitcnt lgkmcnt(0)
	s_setprio 0
	s_barrier
	v_mfma_f32_32x32x16_bf16 v[34:49], v[130:133], v[134:137], v[34:49]
	v_mfma_f32_32x32x16_bf16 v[2:17], v[130:133], v[146:149], v[2:17]
	v_add_u32_e32 v130, s6, v183
	v_ashrrev_i32_e32 v131, 31, v130
	v_lshlrev_b64 v[132:133], 10, v[130:131]
	v_lshl_add_u64 v[132:133], s[2:3], 0, v[132:133]
	v_lshl_add_u64 v[132:133], v[132:133], 0, v[0:1]
	v_lshl_add_u64 v[132:133], v[132:133], 0, v[180:181]
	v_mfma_f32_32x32x16_bf16 v[114:129], v[142:145], v[138:141], v[114:129]
	v_mfma_f32_32x32x16_bf16 v[98:113], v[154:157], v[138:141], v[98:113]
	s_nop 10
	global_store_dwordx4 v[132:133], v[114:117], off
	global_store_dwordx4 v[132:133], v[118:121], off offset:32
	global_store_dwordx4 v[132:133], v[122:125], off offset:64
	global_store_dwordx4 v[132:133], v[126:129], off offset:96
	global_store_dwordx4 v[132:133], v[98:101], off offset:128
	global_store_dwordx4 v[132:133], v[102:105], off offset:160
	s_nop 0
	v_or_b32_e32 v98, 32, v130
	v_ashrrev_i32_e32 v99, 31, v98
	v_lshlrev_b64 v[98:99], 10, v[98:99]
	v_mfma_f32_32x32x16_bf16 v[82:97], v[142:145], v[150:153], v[82:97]
	v_lshl_add_u64 v[98:99], s[2:3], 0, v[98:99]
	v_lshl_add_u64 v[98:99], v[98:99], 0, v[0:1]
	v_lshl_add_u64 v[98:99], v[98:99], 0, v[180:181]
	global_store_dwordx4 v[132:133], v[106:109], off offset:192
	global_store_dwordx4 v[132:133], v[110:113], off offset:224
	v_mfma_f32_32x32x16_bf16 v[66:81], v[154:157], v[150:153], v[66:81]
	s_nop 5
	global_store_dwordx4 v[98:99], v[82:85], off
	global_store_dwordx4 v[98:99], v[86:89], off offset:32
	global_store_dwordx4 v[98:99], v[90:93], off offset:64
	global_store_dwordx4 v[98:99], v[94:97], off offset:96
	s_nop 1
	global_store_dwordx4 v[98:99], v[66:69], off offset:128
	global_store_dwordx4 v[98:99], v[70:73], off offset:160
	v_mfma_f32_32x32x16_bf16 v[34:49], v[162:165], v[138:141], v[34:49]
	v_mfma_f32_32x32x16_bf16 v[2:17], v[162:165], v[150:153], v[2:17]
	v_mfma_f32_32x32x16_bf16 v[50:65], v[158:161], v[138:141], v[50:65]
	global_store_dwordx4 v[98:99], v[74:77], off offset:192
	global_store_dwordx4 v[98:99], v[78:81], off offset:224
	s_nop 9
	global_store_dwordx4 v[132:133], v[50:53], off offset:256
	global_store_dwordx4 v[132:133], v[54:57], off offset:288
	global_store_dwordx4 v[132:133], v[58:61], off offset:320
	global_store_dwordx4 v[132:133], v[62:65], off offset:352
	global_store_dwordx4 v[132:133], v[34:37], off offset:384
	v_mfma_f32_32x32x16_bf16 v[18:33], v[158:161], v[150:153], v[18:33]
	global_store_dwordx4 v[132:133], v[38:41], off offset:416
	global_store_dwordx4 v[132:133], v[42:45], off offset:448
	global_store_dwordx4 v[132:133], v[46:49], off offset:480
	s_nop 8
	global_store_dwordx4 v[98:99], v[18:21], off offset:256
	global_store_dwordx4 v[98:99], v[22:25], off offset:288
	global_store_dwordx4 v[98:99], v[26:29], off offset:320
	global_store_dwordx4 v[98:99], v[30:33], off offset:352
	global_store_dwordx4 v[98:99], v[2:5], off offset:384
	global_store_dwordx4 v[98:99], v[6:9], off offset:416
	global_store_dwordx4 v[98:99], v[10:13], off offset:448
	global_store_dwordx4 v[98:99], v[14:17], off offset:480

.LBB0_728:
	s_or_b64 exec, exec, s[46:47]
	s_lshl_b32 s3, s13, 7
	s_ashr_i32 s23, s22, 31
	s_add_i32 s2, s22, s5
	s_and_b32 s14, s3, 0x780
	s_lshl_b64 s[16:17], s[22:23], 20
	s_add_u32 s16, s40, s16
	s_addc_u32 s17, s41, s17
	s_ashr_i32 s3, s2, 31
	v_mov_b32_e32 v95, v206
	s_waitcnt vmcnt(0)
	s_setprio 0
	s_barrier
	s_lshl_b64 s[2:3], s[2:3], 17
	s_add_u32 s2, s9, s2
	v_ashrrev_i32_e32 v50, 3, v95
	v_ashrrev_i32_e32 v51, 31, v50
	s_addc_u32 s3, s10, s3
	v_lshlrev_b32_e32 v0, 4, v95
	v_lshlrev_b64 v[2:3], 9, v[50:51]
	v_and_b32_e32 v0, 0x70, v0
	v_lshl_add_u64 v[2:3], s[2:3], 0, v[2:3]
	v_lshl_add_u64 v[66:67], v[2:3], 0, v[0:1]
	s_movk_i32 s2, 0x4000
	v_add_co_u32_e32 v68, vcc, s2, v66
	s_mov_b32 s2, 0x8000
	s_nop 0
	v_addc_co_u32_e32 v69, vcc, 0, v67, vcc
	v_add_co_u32_e32 v70, vcc, s2, v66
	s_mov_b32 s2, 0xc000
	s_nop 0
	v_addc_co_u32_e32 v71, vcc, 0, v67, vcc
	v_add_co_u32_e32 v72, vcc, s2, v66
	s_mov_b32 s2, 0x14000
	s_nop 0
	v_addc_co_u32_e32 v73, vcc, 0, v67, vcc
	v_add_co_u32_e32 v74, vcc, s26, v66
	v_add_u32_e32 v28, s14, v50
	s_nop 0
	v_addc_co_u32_e32 v75, vcc, 0, v67, vcc
	v_add_co_u32_e32 v76, vcc, s2, v66
	s_or_b32 s2, s14, 32
	v_ashrrev_i32_e32 v29, 31, v28
	s_sub_u32 s2, s2, s14
	v_lshl_add_u64 v[26:27], s[16:17], 0, v[0:1]
	v_lshlrev_b64 v[28:29], 9, v[28:29]
	s_subb_u32 s3, 0, 0
	v_lshl_add_u64 v[80:81], v[26:27], 0, v[28:29]
	s_lshl_b64 s[2:3], s[2:3], 9
	v_lshl_add_u64 v[90:91], v[80:81], 0, s[2:3]
	v_lshl_add_u64 v[88:89], v[90:91], 0, s[2:3]
	v_addc_co_u32_e32 v77, vcc, 0, v67, vcc
	v_lshl_add_u64 v[92:93], v[88:89], 0, s[2:3]
	s_mov_b32 s2, 0x18000
	v_add_co_u32_e32 v84, vcc, s2, v66
	s_mov_b32 s2, 0x1c000
	s_nop 0
	v_addc_co_u32_e32 v85, vcc, 0, v67, vcc
	v_add_co_u32_e32 v86, vcc, s2, v66
	global_load_dwordx4 v[2:5], v[66:67], off
	global_load_dwordx4 v[6:9], v[68:69], off
	global_load_dwordx4 v[10:13], v[70:71], off
	global_load_dwordx4 v[14:17], v[72:73], off
	global_load_dwordx4 v[18:21], v[74:75], off
	global_load_dwordx4 v[22:25], v[76:77], off
	global_load_dwordx4 v[26:29], v[80:81], off
	global_load_dwordx4 v[30:33], v[90:91], off
	global_load_dwordx4 v[34:37], v[88:89], off
	global_load_dwordx4 v[38:41], v[92:93], off
	v_addc_co_u32_e32 v87, vcc, 0, v67, vcc
	global_load_dwordx4 v[42:45], v[84:85], off
	global_load_dwordx4 v[46:49], v[86:87], off
	v_ashrrev_i32_e32 v97, 6, v95
	v_and_b32_e32 v94, 31, v95
	v_lshrrev_b32_e32 v51, 1, v95
	v_and_b32_e32 v99, 1, v97
	s_movk_i32 s15, 0x90
	v_and_b32_e32 v52, 16, v51
	v_mad_u64_u32 v[82:83], s[2:3], v50, s15, v[0:1]
	v_lshl_or_b32 v0, v99, 7, v94
	v_mad_u32_u24 v0, v0, s15, v52
	s_setprio 0
	s_barrier
	v_ashrrev_i32_e32 v98, 1, v95
	v_and_b32_e32 v96, 0xffffffc0, v98
	s_movk_i32 s21, 0x90
	v_cmp_eq_u32_e32 vcc, 0, v99
	s_waitcnt vmcnt(5)
	ds_write_b128 v82, v[26:29]
	ds_write_b128 v82, v[2:5] offset:18432
	s_waitcnt vmcnt(4)
	ds_write_b128 v82, v[30:33] offset:4608
	s_waitcnt vmcnt(3)
	ds_write_b128 v82, v[34:37] offset:9216
	s_waitcnt vmcnt(2)
	ds_write_b128 v82, v[38:41] offset:13824
	ds_write_b128 v82, v[6:9] offset:23040
	ds_write_b128 v82, v[10:13] offset:27648
	ds_write_b128 v82, v[14:17] offset:32256
	ds_write_b128 v82, v[18:21] offset:36864
	ds_write_b128 v82, v[22:25] offset:41472
	s_waitcnt vmcnt(1)
	ds_write_b128 v82, v[42:45] offset:46080
	s_waitcnt vmcnt(0)
	ds_write_b128 v82, v[46:49] offset:50688
	s_waitcnt lgkmcnt(0)
	s_setprio 0
	s_barrier
	s_setprio 0
	ds_read_b128 v[2:5], v0 offset:18432
	v_or_b32_e32 v6, v96, v94
	v_mad_u64_u32 v[78:79], s[2:3], v6, s15, v[52:53]
	ds_read_b128 v[6:9], v78
	ds_read_b128 v[100:103], v78 offset:32
	ds_read_b128 v[104:107], v0 offset:18464
	ds_read_b128 v[34:37], v78 offset:4608
	ds_read_b128 v[108:111], v78 offset:4640
	s_waitcnt lgkmcnt(4)
	v_mfma_f32_32x32x16_bf16 v[18:33], v[2:5], v[6:9], 0
	ds_read_b128 v[38:41], v0 offset:23040
	ds_read_b128 v[112:115], v0 offset:23072
	s_waitcnt lgkmcnt(3)
	v_mfma_f32_32x32x16_bf16 v[50:65], v[2:5], v[34:37], 0
	s_waitcnt lgkmcnt(1)
	v_mfma_f32_32x32x16_bf16 v[2:17], v[38:41], v[6:9], 0
	v_mfma_f32_32x32x16_bf16 v[34:49], v[38:41], v[34:37], 0
	v_mfma_f32_32x32x16_bf16 v[18:33], v[104:107], v[100:103], v[18:33]
	v_mfma_f32_32x32x16_bf16 v[50:65], v[104:107], v[108:111], v[50:65]
	s_waitcnt lgkmcnt(0)
	v_mfma_f32_32x32x16_bf16 v[2:17], v[112:115], v[100:103], v[2:17]
	v_mfma_f32_32x32x16_bf16 v[34:49], v[112:115], v[108:111], v[34:49]
	ds_read_b128 v[100:103], v0 offset:18496
	ds_read_b128 v[104:107], v78 offset:64
	ds_read_b128 v[108:111], v78 offset:96
	ds_read_b128 v[112:115], v0 offset:18528
	ds_read_b128 v[116:119], v78 offset:4672
	ds_read_b128 v[120:123], v78 offset:4704
	s_waitcnt lgkmcnt(4)
	v_mfma_f32_32x32x16_bf16 v[18:33], v[100:103], v[104:107], v[18:33]
	s_waitcnt lgkmcnt(1)
	v_mfma_f32_32x32x16_bf16 v[50:65], v[100:103], v[116:119], v[50:65]
	ds_read_b128 v[100:103], v0 offset:23104
	ds_read_b128 v[124:127], v0 offset:23136
	s_waitcnt lgkmcnt(1)
	v_mfma_f32_32x32x16_bf16 v[2:17], v[100:103], v[104:107], v[2:17]
	v_mfma_f32_32x32x16_bf16 v[34:49], v[100:103], v[116:119], v[34:49]
	global_load_dwordx4 v[100:103], v[90:91], off offset:128
	global_load_dwordx4 v[104:107], v[80:81], off offset:128
	v_mfma_f32_32x32x16_bf16 v[18:33], v[112:115], v[108:111], v[18:33]
	v_mfma_f32_32x32x16_bf16 v[50:65], v[112:115], v[120:123], v[50:65]
	global_load_dwordx4 v[112:115], v[92:93], off offset:128
	global_load_dwordx4 v[116:119], v[88:89], off offset:128
	global_load_dwordx4 v[128:131], v[68:69], off offset:128
	global_load_dwordx4 v[132:135], v[66:67], off offset:128
	global_load_dwordx4 v[136:139], v[72:73], off offset:128
	global_load_dwordx4 v[140:143], v[70:71], off offset:128
	global_load_dwordx4 v[144:147], v[76:77], off offset:128
	global_load_dwordx4 v[148:151], v[74:75], off offset:128
	s_waitcnt lgkmcnt(0)
	v_mfma_f32_32x32x16_bf16 v[2:17], v[124:127], v[108:111], v[2:17]
	global_load_dwordx4 v[108:111], v[84:85], off offset:128
	global_load_dwordx4 v[152:155], v[86:87], off offset:128
	s_setprio 0
	s_barrier
	s_waitcnt vmcnt(10)
	ds_write_b128 v82, v[104:107]
	ds_write_b128 v82, v[100:103] offset:4608
	s_waitcnt vmcnt(8)
	ds_write_b128 v82, v[116:119] offset:9216
	ds_write_b128 v82, v[112:115] offset:13824
	s_waitcnt vmcnt(6)
	ds_write_b128 v82, v[132:135] offset:18432
	ds_write_b128 v82, v[128:131] offset:23040
	s_waitcnt vmcnt(4)
	ds_write_b128 v82, v[140:143] offset:27648
	ds_write_b128 v82, v[136:139] offset:32256
	s_waitcnt vmcnt(2)
	ds_write_b128 v82, v[148:151] offset:36864
	ds_write_b128 v82, v[144:147] offset:41472
	s_waitcnt vmcnt(1)
	ds_write_b128 v82, v[108:111] offset:46080
	s_waitcnt vmcnt(0)
	ds_write_b128 v82, v[152:155] offset:50688
	v_mfma_f32_32x32x16_bf16 v[34:49], v[124:127], v[120:123], v[34:49]
	s_waitcnt lgkmcnt(0)
	s_setprio 0
	s_barrier
	ds_read_b128 v[100:103], v0 offset:18432
	ds_read_b128 v[104:107], v78
	ds_read_b128 v[108:111], v78 offset:32
	ds_read_b128 v[112:115], v0 offset:18464
	ds_read_b128 v[116:119], v78 offset:4608
	ds_read_b128 v[120:123], v78 offset:4640
	s_waitcnt lgkmcnt(4)
	v_mfma_f32_32x32x16_bf16 v[18:33], v[100:103], v[104:107], v[18:33]
	s_waitcnt lgkmcnt(1)
	v_mfma_f32_32x32x16_bf16 v[50:65], v[100:103], v[116:119], v[50:65]
	ds_read_b128 v[100:103], v0 offset:23040
	ds_read_b128 v[124:127], v0 offset:23072
	s_waitcnt lgkmcnt(1)
	v_mfma_f32_32x32x16_bf16 v[2:17], v[100:103], v[104:107], v[2:17]
	v_mfma_f32_32x32x16_bf16 v[34:49], v[100:103], v[116:119], v[34:49]
	v_mfma_f32_32x32x16_bf16 v[18:33], v[112:115], v[108:111], v[18:33]
	v_mfma_f32_32x32x16_bf16 v[50:65], v[112:115], v[120:123], v[50:65]
	s_waitcnt lgkmcnt(0)
	v_mfma_f32_32x32x16_bf16 v[2:17], v[124:127], v[108:111], v[2:17]
	ds_read_b128 v[100:103], v0 offset:18496
	ds_read_b128 v[104:107], v78 offset:64
	ds_read_b128 v[108:111], v78 offset:96
	ds_read_b128 v[112:115], v0 offset:18528
	v_mfma_f32_32x32x16_bf16 v[34:49], v[124:127], v[120:123], v[34:49]
	ds_read_b128 v[116:119], v78 offset:4672
	ds_read_b128 v[120:123], v78 offset:4704
	s_waitcnt lgkmcnt(4)
	v_mfma_f32_32x32x16_bf16 v[18:33], v[100:103], v[104:107], v[18:33]
	s_waitcnt lgkmcnt(1)
	v_mfma_f32_32x32x16_bf16 v[50:65], v[100:103], v[116:119], v[50:65]
	ds_read_b128 v[100:103], v0 offset:23104
	ds_read_b128 v[124:127], v0 offset:23136
	s_waitcnt lgkmcnt(1)
	v_mfma_f32_32x32x16_bf16 v[2:17], v[100:103], v[104:107], v[2:17]
	v_mfma_f32_32x32x16_bf16 v[34:49], v[100:103], v[116:119], v[34:49]
	global_load_dwordx4 v[100:103], v[90:91], off offset:256
	global_load_dwordx4 v[104:107], v[80:81], off offset:256
	v_mfma_f32_32x32x16_bf16 v[18:33], v[112:115], v[108:111], v[18:33]
	v_mfma_f32_32x32x16_bf16 v[50:65], v[112:115], v[120:123], v[50:65]
	global_load_dwordx4 v[112:115], v[92:93], off offset:256
	global_load_dwordx4 v[116:119], v[88:89], off offset:256
	global_load_dwordx4 v[128:131], v[68:69], off offset:256
	global_load_dwordx4 v[132:135], v[66:67], off offset:256
	global_load_dwordx4 v[136:139], v[72:73], off offset:256
	global_load_dwordx4 v[140:143], v[70:71], off offset:256
	global_load_dwordx4 v[144:147], v[76:77], off offset:256
	global_load_dwordx4 v[148:151], v[74:75], off offset:256
	s_waitcnt lgkmcnt(0)
	v_mfma_f32_32x32x16_bf16 v[2:17], v[124:127], v[108:111], v[2:17]
	global_load_dwordx4 v[108:111], v[84:85], off offset:256
	global_load_dwordx4 v[152:155], v[86:87], off offset:256
	s_setprio 0
	s_barrier
	s_waitcnt vmcnt(10)
	ds_write_b128 v82, v[104:107]
	ds_write_b128 v82, v[100:103] offset:4608
	s_waitcnt vmcnt(8)
	ds_write_b128 v82, v[116:119] offset:9216
	ds_write_b128 v82, v[112:115] offset:13824
	s_waitcnt vmcnt(6)
	ds_write_b128 v82, v[132:135] offset:18432
	ds_write_b128 v82, v[128:131] offset:23040
	s_waitcnt vmcnt(4)
	ds_write_b128 v82, v[140:143] offset:27648
	ds_write_b128 v82, v[136:139] offset:32256
	s_waitcnt vmcnt(2)
	ds_write_b128 v82, v[148:151] offset:36864
	ds_write_b128 v82, v[144:147] offset:41472
	s_waitcnt vmcnt(1)
	ds_write_b128 v82, v[108:111] offset:46080
	s_waitcnt vmcnt(0)
	ds_write_b128 v82, v[152:155] offset:50688
	v_mfma_f32_32x32x16_bf16 v[34:49], v[124:127], v[120:123], v[34:49]
	s_waitcnt lgkmcnt(0)
	s_setprio 0
	s_barrier
	ds_read_b128 v[100:103], v0 offset:18432
	ds_read_b128 v[104:107], v78
	ds_read_b128 v[108:111], v78 offset:32
	ds_read_b128 v[112:115], v0 offset:18464
	ds_read_b128 v[116:119], v78 offset:4608
	ds_read_b128 v[120:123], v78 offset:4640
	s_waitcnt lgkmcnt(4)
	v_mfma_f32_32x32x16_bf16 v[18:33], v[100:103], v[104:107], v[18:33]
	s_waitcnt lgkmcnt(1)
	v_mfma_f32_32x32x16_bf16 v[50:65], v[100:103], v[116:119], v[50:65]
	ds_read_b128 v[100:103], v0 offset:23040
	ds_read_b128 v[124:127], v0 offset:23072
	s_waitcnt lgkmcnt(1)
	v_mfma_f32_32x32x16_bf16 v[2:17], v[100:103], v[104:107], v[2:17]
	v_mfma_f32_32x32x16_bf16 v[34:49], v[100:103], v[116:119], v[34:49]
	v_mfma_f32_32x32x16_bf16 v[18:33], v[112:115], v[108:111], v[18:33]
	v_mfma_f32_32x32x16_bf16 v[50:65], v[112:115], v[120:123], v[50:65]
	s_waitcnt lgkmcnt(0)
	v_mfma_f32_32x32x16_bf16 v[2:17], v[124:127], v[108:111], v[2:17]
	ds_read_b128 v[100:103], v0 offset:18496
	ds_read_b128 v[104:107], v78 offset:64
	ds_read_b128 v[108:111], v78 offset:96
	ds_read_b128 v[112:115], v0 offset:18528
	v_mfma_f32_32x32x16_bf16 v[34:49], v[124:127], v[120:123], v[34:49]
	ds_read_b128 v[116:119], v78 offset:4672
	ds_read_b128 v[120:123], v78 offset:4704
	s_waitcnt lgkmcnt(4)
	v_mfma_f32_32x32x16_bf16 v[18:33], v[100:103], v[104:107], v[18:33]
	s_waitcnt lgkmcnt(1)
	v_mfma_f32_32x32x16_bf16 v[50:65], v[100:103], v[116:119], v[50:65]
	ds_read_b128 v[100:103], v0 offset:23104
	ds_read_b128 v[124:127], v0 offset:23136
	s_waitcnt lgkmcnt(1)
	v_mfma_f32_32x32x16_bf16 v[2:17], v[100:103], v[104:107], v[2:17]
	v_mfma_f32_32x32x16_bf16 v[34:49], v[100:103], v[116:119], v[34:49]
	global_load_dwordx4 v[100:103], v[90:91], off offset:384
	global_load_dwordx4 v[104:107], v[80:81], off offset:384
	v_mfma_f32_32x32x16_bf16 v[18:33], v[112:115], v[108:111], v[18:33]
	v_mfma_f32_32x32x16_bf16 v[50:65], v[112:115], v[120:123], v[50:65]
	global_load_dwordx4 v[90:93], v[92:93], off offset:384
	s_nop 0
	global_load_dwordx4 v[112:115], v[88:89], off offset:384
	global_load_dwordx4 v[116:119], v[68:69], off offset:384
	s_nop 0
	global_load_dwordx4 v[66:69], v[66:67], off offset:384
	s_nop 0
	global_load_dwordx4 v[128:131], v[72:73], off offset:384
	s_nop 0
	global_load_dwordx4 v[70:73], v[70:71], off offset:384
	s_nop 0
	global_load_dwordx4 v[132:135], v[76:77], off offset:384
	s_nop 0
	global_load_dwordx4 v[74:77], v[74:75], off offset:384
	s_waitcnt lgkmcnt(0)
	v_mfma_f32_32x32x16_bf16 v[2:17], v[124:127], v[108:111], v[2:17]
	global_load_dwordx4 v[108:111], v[84:85], off offset:384
	s_nop 0
	global_load_dwordx4 v[84:87], v[86:87], off offset:384
	s_setprio 0
	s_barrier
	s_waitcnt vmcnt(10)
	ds_write_b128 v82, v[104:107]
	ds_write_b128 v82, v[100:103] offset:4608
	s_waitcnt vmcnt(8)
	ds_write_b128 v82, v[112:115] offset:9216
	ds_write_b128 v82, v[90:93] offset:13824
	s_waitcnt vmcnt(6)
	ds_write_b128 v82, v[66:69] offset:18432
	ds_write_b128 v82, v[116:119] offset:23040
	s_waitcnt vmcnt(4)
	ds_write_b128 v82, v[70:73] offset:27648
	ds_write_b128 v82, v[128:131] offset:32256
	s_waitcnt vmcnt(2)
	ds_write_b128 v82, v[74:77] offset:36864
	ds_write_b128 v82, v[132:135] offset:41472
	s_waitcnt vmcnt(1)
	ds_write_b128 v82, v[108:111] offset:46080
	s_waitcnt vmcnt(0)
	ds_write_b128 v82, v[84:87] offset:50688
	v_mfma_f32_32x32x16_bf16 v[34:49], v[124:127], v[120:123], v[34:49]
	s_waitcnt lgkmcnt(0)
	s_setprio 0
	s_barrier
	ds_read_b128 v[66:69], v0 offset:18432
	ds_read_b128 v[70:73], v78
	ds_read_b128 v[74:77], v78 offset:32
	ds_read_b128 v[80:83], v0 offset:18464
	ds_read_b128 v[84:87], v78 offset:4608
	ds_read_b128 v[88:91], v78 offset:4640
	s_waitcnt lgkmcnt(4)
	v_mfma_f32_32x32x16_bf16 v[18:33], v[66:69], v[70:73], v[18:33]
	s_waitcnt lgkmcnt(1)
	v_mfma_f32_32x32x16_bf16 v[50:65], v[66:69], v[84:87], v[50:65]
	ds_read_b128 v[66:69], v0 offset:23040
	ds_read_b128 v[100:103], v0 offset:23072
	s_waitcnt lgkmcnt(1)
	v_mfma_f32_32x32x16_bf16 v[2:17], v[66:69], v[70:73], v[2:17]
	v_mfma_f32_32x32x16_bf16 v[34:49], v[66:69], v[84:87], v[34:49]
	v_mfma_f32_32x32x16_bf16 v[18:33], v[80:83], v[74:77], v[18:33]
	v_mfma_f32_32x32x16_bf16 v[50:65], v[80:83], v[88:91], v[50:65]
	s_waitcnt lgkmcnt(0)
	v_mfma_f32_32x32x16_bf16 v[2:17], v[100:103], v[74:77], v[2:17]
	ds_read_b128 v[66:69], v0 offset:18496
	ds_read_b128 v[70:73], v78 offset:64
	ds_read_b128 v[74:77], v78 offset:96
	ds_read_b128 v[80:83], v0 offset:18528
	v_mfma_f32_32x32x16_bf16 v[34:49], v[100:103], v[88:91], v[34:49]
	ds_read_b128 v[84:87], v78 offset:4672
	ds_read_b128 v[88:91], v78 offset:4704
	s_waitcnt lgkmcnt(4)
	v_mfma_f32_32x32x16_bf16 v[18:33], v[66:69], v[70:73], v[18:33]
	s_waitcnt lgkmcnt(1)
	v_mfma_f32_32x32x16_bf16 v[50:65], v[66:69], v[84:87], v[50:65]
	ds_read_b128 v[66:69], v0 offset:23104
	ds_read_b128 v[100:103], v0 offset:23136
	s_waitcnt lgkmcnt(0)
	s_setprio 0
	s_barrier
	v_mfma_f32_32x32x16_bf16 v[2:17], v[66:69], v[70:73], v[2:17]
	v_mfma_f32_32x32x16_bf16 v[34:49], v[66:69], v[84:87], v[34:49]
	v_mfma_f32_32x32x16_bf16 v[18:33], v[80:83], v[74:77], v[18:33]
	v_mfma_f32_32x32x16_bf16 v[50:65], v[80:83], v[88:91], v[50:65]
	v_mfma_f32_32x32x16_bf16 v[2:17], v[100:103], v[74:77], v[2:17]
	v_mfma_f32_32x32x16_bf16 v[34:49], v[100:103], v[88:91], v[34:49]
	s_and_saveexec_b64 s[2:3], vcc
	s_cbranch_execz .LBB0_724
	v_bfe_u32 v71, v95, 3, 3
	s_movk_i32 s15, 0x2400
	v_and_b32_e32 v70, 63, v95
	v_and_b32_e32 v67, 4, v71
	v_mul_lo_u32 v72, v97, s15
	v_and_b32_e32 v73, 64, v98
	v_add_u32_e32 v66, s14, v96
	s_cmp_gt_u32 s13, 15
	s_mov_b64 s[22:23], -1
	s_cbranch_scc0 .LBB0_731
	v_mul_u32_u24_e32 v0, 0x90, v67
	v_lshlrev_b32_e32 v68, 1, v94
	v_add3_u32 v74, v72, v0, v68
	v_ashrrev_i32_e32 v68, 7, v66
	s_movk_i32 s14, 0x5f
	v_ashrrev_i32_e32 v69, 31, v68
	v_bitop3_b32 v0, v96, s14, v70 bitop3:0xc8
	v_lshlrev_b64 v[68:69], 14, v[68:69]
	v_cmp_eq_u32_e32 vcc, s14, v0
	v_lshl_add_u64 v[68:69], s[44:45], 0, v[68:69]
	v_lshlrev_b32_e32 v0, 1, v73
	v_lshl_add_u64 v[68:69], v[68:69], 0, v[0:1]
	v_cvt_pk_bf16_f32 v0, v18, s0
	ds_write_b16 v74, v0
	v_cvt_pk_bf16_f32 v0, v19, s0
	ds_write_b16 v74, v0 offset:144
	v_cvt_pk_bf16_f32 v0, v20, s0
	ds_write_b16 v74, v0 offset:288
	v_cvt_pk_bf16_f32 v0, v21, s0
	ds_write_b16 v74, v0 offset:432
	v_cvt_pk_bf16_f32 v0, v22, s0
	ds_write_b16 v74, v0 offset:1152
	v_cvt_pk_bf16_f32 v0, v23, s0
	ds_write_b16 v74, v0 offset:1296
	v_cvt_pk_bf16_f32 v0, v24, s0
	ds_write_b16 v74, v0 offset:1440
	v_cvt_pk_bf16_f32 v0, v25, s0
	ds_write_b16 v74, v0 offset:1584
	v_cvt_pk_bf16_f32 v0, v26, s0
	ds_write_b16 v74, v0 offset:2304
	v_cvt_pk_bf16_f32 v0, v27, s0
	ds_write_b16 v74, v0 offset:2448
	v_cvt_pk_bf16_f32 v0, v28, s0
	ds_write_b16 v74, v0 offset:2592
	v_cvt_pk_bf16_f32 v0, v29, s0
	ds_write_b16 v74, v0 offset:2736
	v_cvt_pk_bf16_f32 v0, v30, s0
	ds_write_b16 v74, v0 offset:3456
	v_cvt_pk_bf16_f32 v0, v31, s0
	ds_write_b16 v74, v0 offset:3600
	v_cvt_pk_bf16_f32 v0, v32, s0
	ds_write_b16 v74, v0 offset:3744
	v_cvt_pk_bf16_f32 v0, v33, s0
	ds_write_b16 v74, v0 offset:3888
	v_cvt_pk_bf16_f32 v0, v2, s0
	ds_write_b16 v74, v0 offset:4608
	v_cvt_pk_bf16_f32 v0, v3, s0
	ds_write_b16 v74, v0 offset:4752
	v_cvt_pk_bf16_f32 v0, v4, s0
	ds_write_b16 v74, v0 offset:4896
	v_cvt_pk_bf16_f32 v0, v5, s0
	ds_write_b16 v74, v0 offset:5040
	v_cvt_pk_bf16_f32 v0, v6, s0
	ds_write_b16 v74, v0 offset:5760
	v_cvt_pk_bf16_f32 v0, v7, s0
	ds_write_b16 v74, v0 offset:5904
	v_cvt_pk_bf16_f32 v0, v8, s0
	ds_write_b16 v74, v0 offset:6048
	v_cvt_pk_bf16_f32 v0, v9, s0
	ds_write_b16 v74, v0 offset:6192
	v_cvt_pk_bf16_f32 v0, v10, s0
	ds_write_b16 v74, v0 offset:6912
	v_cvt_pk_bf16_f32 v0, v11, s0
	ds_write_b16 v74, v0 offset:7056
	v_cvt_pk_bf16_f32 v0, v12, s0
	ds_write_b16 v74, v0 offset:7200
	v_cvt_pk_bf16_f32 v0, v13, s0
	ds_write_b16 v74, v0 offset:7344
	v_cvt_pk_bf16_f32 v0, v14, s0
	ds_write_b16 v74, v0 offset:8064
	v_cvt_pk_bf16_f32 v0, v15, s0
	ds_write_b16 v74, v0 offset:8208
	v_cvt_pk_bf16_f32 v0, v16, s0
	ds_write_b16 v74, v0 offset:8352
	v_cvt_pk_bf16_f32 v0, v17, s0
	ds_write_b16 v74, v0 offset:8496
	v_cvt_pk_bf16_f32 v0, v50, s0
	v_cndmask_b32_e64 v0, v0, 0, vcc
	ds_write_b16 v74, v0 offset:64
	v_cvt_pk_bf16_f32 v0, v51, s0
	v_cndmask_b32_e64 v0, v0, 0, vcc
	ds_write_b16 v74, v0 offset:208
	v_cvt_pk_bf16_f32 v0, v52, s0
	v_cndmask_b32_e64 v0, v0, 0, vcc
	ds_write_b16 v74, v0 offset:352
	v_cvt_pk_bf16_f32 v0, v53, s0
	v_cndmask_b32_e64 v0, v0, 0, vcc
	ds_write_b16 v74, v0 offset:496
	v_cvt_pk_bf16_f32 v0, v54, s0
	v_cndmask_b32_e64 v0, v0, 0, vcc
	ds_write_b16 v74, v0 offset:1216
	v_cvt_pk_bf16_f32 v0, v55, s0
	v_cndmask_b32_e64 v0, v0, 0, vcc
	ds_write_b16 v74, v0 offset:1360
	v_cvt_pk_bf16_f32 v0, v56, s0
	v_cndmask_b32_e64 v0, v0, 0, vcc
	ds_write_b16 v74, v0 offset:1504
	v_cvt_pk_bf16_f32 v0, v57, s0
	v_cndmask_b32_e64 v0, v0, 0, vcc
	ds_write_b16 v74, v0 offset:1648
	v_cvt_pk_bf16_f32 v0, v58, s0
	v_cndmask_b32_e64 v0, v0, 0, vcc
	ds_write_b16 v74, v0 offset:2368
	v_cvt_pk_bf16_f32 v0, v59, s0
	v_cndmask_b32_e64 v0, v0, 0, vcc
	ds_write_b16 v74, v0 offset:2512
	v_cvt_pk_bf16_f32 v0, v60, s0
	v_cndmask_b32_e64 v0, v0, 0, vcc
	ds_write_b16 v74, v0 offset:2656
	v_cvt_pk_bf16_f32 v0, v61, s0
	v_cndmask_b32_e64 v0, v0, 0, vcc
	ds_write_b16 v74, v0 offset:2800
	v_cvt_pk_bf16_f32 v0, v62, s0
	v_cndmask_b32_e64 v0, v0, 0, vcc
	ds_write_b16 v74, v0 offset:3520
	v_cvt_pk_bf16_f32 v0, v63, s0
	v_cndmask_b32_e64 v0, v0, 0, vcc
	ds_write_b16 v74, v0 offset:3664
	v_cvt_pk_bf16_f32 v0, v64, s0
	v_cndmask_b32_e64 v0, v0, 0, vcc
	ds_write_b16 v74, v0 offset:3808
	v_cvt_pk_bf16_f32 v0, v65, s0
	v_cndmask_b32_e64 v0, v0, 0, vcc
	ds_write_b16 v74, v0 offset:3952
	v_cvt_pk_bf16_f32 v0, v34, s0
	v_cndmask_b32_e64 v0, v0, 0, vcc
	ds_write_b16 v74, v0 offset:4672
	v_cvt_pk_bf16_f32 v0, v35, s0
	v_cndmask_b32_e64 v0, v0, 0, vcc
	ds_write_b16 v74, v0 offset:4816
	v_cvt_pk_bf16_f32 v0, v36, s0
	v_cndmask_b32_e64 v0, v0, 0, vcc
	ds_write_b16 v74, v0 offset:4960
	v_cvt_pk_bf16_f32 v0, v37, s0
	v_cndmask_b32_e64 v0, v0, 0, vcc
	ds_write_b16 v74, v0 offset:5104
	v_cvt_pk_bf16_f32 v0, v38, s0
	v_cndmask_b32_e64 v0, v0, 0, vcc
	ds_write_b16 v74, v0 offset:5824
	v_cvt_pk_bf16_f32 v0, v39, s0
	v_cndmask_b32_e64 v0, v0, 0, vcc
	ds_write_b16 v74, v0 offset:5968
	v_cvt_pk_bf16_f32 v0, v40, s0
	v_cndmask_b32_e64 v0, v0, 0, vcc
	ds_write_b16 v74, v0 offset:6112
	v_cvt_pk_bf16_f32 v0, v41, s0
	v_cndmask_b32_e64 v0, v0, 0, vcc
	ds_write_b16 v74, v0 offset:6256
	v_cvt_pk_bf16_f32 v0, v42, s0
	v_cndmask_b32_e64 v0, v0, 0, vcc
	ds_write_b16 v74, v0 offset:6976
	v_cvt_pk_bf16_f32 v0, v43, s0
	v_cndmask_b32_e64 v0, v0, 0, vcc
	ds_write_b16 v74, v0 offset:7120
	v_cvt_pk_bf16_f32 v0, v44, s0
	v_cndmask_b32_e64 v0, v0, 0, vcc
	ds_write_b16 v74, v0 offset:7264
	v_cvt_pk_bf16_f32 v0, v45, s0
	v_cndmask_b32_e64 v0, v0, 0, vcc
	ds_write_b16 v74, v0 offset:7408
	v_cvt_pk_bf16_f32 v0, v46, s0
	v_cndmask_b32_e64 v0, v0, 0, vcc
	ds_write_b16 v74, v0 offset:8128
	v_cvt_pk_bf16_f32 v0, v47, s0
	v_cndmask_b32_e64 v0, v0, 0, vcc
	ds_write_b16 v74, v0 offset:8272
	v_cvt_pk_bf16_f32 v0, v48, s0
	v_cndmask_b32_e64 v0, v0, 0, vcc
	ds_write_b16 v74, v0 offset:8416
	v_cvt_pk_bf16_f32 v0, v49, s0
	v_cndmask_b32_e64 v0, v0, 0, vcc
	ds_write_b16 v74, v0 offset:8560
	v_lshlrev_b32_e32 v0, 8, v71
	v_lshl_add_u64 v[68:69], v[68:69], 0, v[0:1]
	s_mov_b64 s[22:23], 0

.LBB0_814:
	s_or_b64 exec, exec, s[36:37]
	s_and_b32 s2, s19, -2
	s_ashr_i32 s19, s18, 31
	s_add_i32 s2, s18, s2
	s_lshl_b64 s[6:7], s[18:19], 20
	s_add_u32 s6, s22, s6
	s_addc_u32 s7, s23, s7
	s_ashr_i32 s3, s2, 31
	v_mov_b32_e32 v93, v206
	s_waitcnt vmcnt(0)
	s_setprio 0
	s_barrier
	s_lshl_b64 s[2:3], s[2:3], 17
	s_add_u32 s2, s34, s2
	v_ashrrev_i32_e32 v50, 3, v93
	v_ashrrev_i32_e32 v51, 31, v50
	s_addc_u32 s3, s35, s3
	v_lshlrev_b32_e32 v0, 4, v93
	v_lshlrev_b64 v[2:3], 9, v[50:51]
	v_and_b32_e32 v0, 0x70, v0
	v_lshl_add_u64 v[2:3], s[2:3], 0, v[2:3]
	s_waitcnt vmcnt(9)
	v_lshl_add_u64 v[124:125], v[2:3], 0, v[0:1]
	s_mov_b32 s2, 0xc800000
	v_add_co_u32_e32 v2, vcc, s2, v124
	s_mov_b32 s2, 0xc804000
	s_nop 0
	v_addc_co_u32_e32 v3, vcc, 0, v125, vcc
	v_add_co_u32_e32 v66, vcc, s2, v124
	s_mov_b32 s2, 0xc808000
	s_nop 0
	v_addc_co_u32_e32 v67, vcc, 0, v125, vcc
	v_add_co_u32_e32 v68, vcc, s2, v124
	s_mov_b32 s2, 0xc80c000
	s_nop 0
	v_addc_co_u32_e32 v69, vcc, 0, v125, vcc
	v_add_co_u32_e32 v70, vcc, s2, v124
	s_mov_b32 s2, 0xc810000
	s_nop 0
	v_addc_co_u32_e32 v71, vcc, 0, v125, vcc
	v_add_co_u32_e32 v72, vcc, s2, v124
	s_mov_b32 s2, 0xc814000
	s_nop 0
	v_addc_co_u32_e32 v73, vcc, 0, v125, vcc
	v_add_co_u32_e32 v74, vcc, s2, v124
	v_add_u32_e32 v28, s4, v50
	s_or_b32 s2, s4, 32
	v_ashrrev_i32_e32 v29, 31, v28
	s_sub_u32 s2, s2, s4
	v_lshl_add_u64 v[26:27], s[6:7], 0, v[0:1]
	v_lshlrev_b64 v[28:29], 9, v[28:29]
	s_subb_u32 s3, 0, 0
	v_lshl_add_u64 v[80:81], v[26:27], 0, v[28:29]
	s_lshl_b64 s[2:3], s[2:3], 9
	v_lshl_add_u64 v[88:89], v[80:81], 0, s[2:3]
	v_lshl_add_u64 v[86:87], v[88:89], 0, s[2:3]
	v_addc_co_u32_e32 v75, vcc, 0, v125, vcc
	v_lshl_add_u64 v[90:91], v[86:87], 0, s[2:3]
	s_mov_b32 s2, 0xc818000
	v_add_co_u32_e32 v82, vcc, s2, v124
	s_mov_b32 s2, 0xc81c000
	s_nop 0
	v_addc_co_u32_e32 v83, vcc, 0, v125, vcc
	v_add_co_u32_e32 v84, vcc, s2, v124
	global_load_dwordx4 v[2:5], v[2:3], off
	s_nop 0
	global_load_dwordx4 v[6:9], v[66:67], off
	global_load_dwordx4 v[10:13], v[68:69], off
	global_load_dwordx4 v[14:17], v[70:71], off
	global_load_dwordx4 v[18:21], v[72:73], off
	global_load_dwordx4 v[22:25], v[74:75], off
	global_load_dwordx4 v[26:29], v[80:81], off
	global_load_dwordx4 v[30:33], v[88:89], off
	global_load_dwordx4 v[34:37], v[86:87], off
	global_load_dwordx4 v[38:41], v[90:91], off
	v_addc_co_u32_e32 v85, vcc, 0, v125, vcc
	global_load_dwordx4 v[42:45], v[82:83], off
	global_load_dwordx4 v[46:49], v[84:85], off
	v_ashrrev_i32_e32 v94, 6, v93
	s_movk_i32 s5, 0x90
	v_and_b32_e32 v95, 1, v94
	v_and_b32_e32 v92, 31, v93
	v_mad_u64_u32 v[78:79], s[2:3], v50, s5, v[0:1]
	v_lshrrev_b32_e32 v50, 1, v93
	v_and_b32_e32 v50, 16, v50
	v_lshl_or_b32 v51, v95, 7, v92
	v_mad_u32_u24 v154, v51, s5, v50
	s_setprio 0
	s_barrier
	v_ashrrev_i32_e32 v79, 1, v93
	v_and_b32_e32 v0, 0xffffffc0, v79
	s_movk_i32 s21, 0x90
	v_cmp_eq_u32_e32 vcc, 0, v95
	s_waitcnt vmcnt(5)
	ds_write_b128 v78, v[26:29]
	s_waitcnt vmcnt(4)
	ds_write_b128 v78, v[30:33] offset:4608
	s_waitcnt vmcnt(3)
	ds_write_b128 v78, v[34:37] offset:9216
	s_waitcnt vmcnt(2)
	ds_write_b128 v78, v[38:41] offset:13824
	ds_write_b128 v78, v[2:5] offset:18432
	ds_write_b128 v78, v[6:9] offset:23040
	ds_write_b128 v78, v[10:13] offset:27648
	ds_write_b128 v78, v[14:17] offset:32256
	ds_write_b128 v78, v[18:21] offset:36864
	ds_write_b128 v78, v[22:25] offset:41472
	s_waitcnt vmcnt(1)
	ds_write_b128 v78, v[42:45] offset:46080
	s_waitcnt vmcnt(0)
	ds_write_b128 v78, v[46:49] offset:50688
	s_waitcnt lgkmcnt(0)
	s_setprio 0
	s_barrier
	s_setprio 0
	ds_read_b128 v[2:5], v154 offset:18432
	v_or_b32_e32 v6, v0, v92
	v_mad_u64_u32 v[76:77], s[2:3], v6, s5, v[50:51]
	ds_read_b128 v[6:9], v76
	ds_read_b128 v[96:99], v76 offset:32
	ds_read_b128 v[100:103], v154 offset:18464
	ds_read_b128 v[34:37], v76 offset:4608
	ds_read_b128 v[104:107], v76 offset:4640
	s_waitcnt lgkmcnt(4)
	v_mfma_f32_32x32x16_bf16 v[18:33], v[2:5], v[6:9], 0
	ds_read_b128 v[38:41], v154 offset:23040
	ds_read_b128 v[108:111], v154 offset:23072
	s_mov_b64 s[2:3], 0xc800000
	v_lshl_add_u64 v[152:153], v[124:125], 0, s[2:3]
	s_waitcnt lgkmcnt(3)
	v_mfma_f32_32x32x16_bf16 v[50:65], v[2:5], v[34:37], 0
	s_waitcnt lgkmcnt(1)
	v_mfma_f32_32x32x16_bf16 v[2:17], v[38:41], v[6:9], 0
	v_mfma_f32_32x32x16_bf16 v[34:49], v[38:41], v[34:37], 0
	v_mfma_f32_32x32x16_bf16 v[18:33], v[100:103], v[96:99], v[18:33]
	v_mfma_f32_32x32x16_bf16 v[50:65], v[100:103], v[104:107], v[50:65]
	s_waitcnt lgkmcnt(0)
	v_mfma_f32_32x32x16_bf16 v[2:17], v[108:111], v[96:99], v[2:17]
	v_mfma_f32_32x32x16_bf16 v[34:49], v[108:111], v[104:107], v[34:49]
	ds_read_b128 v[96:99], v154 offset:18496
	ds_read_b128 v[100:103], v76 offset:64
	ds_read_b128 v[104:107], v76 offset:96
	ds_read_b128 v[108:111], v154 offset:18528
	ds_read_b128 v[112:115], v76 offset:4672
	ds_read_b128 v[116:119], v76 offset:4704
	s_waitcnt lgkmcnt(4)
	v_mfma_f32_32x32x16_bf16 v[18:33], v[96:99], v[100:103], v[18:33]
	s_waitcnt lgkmcnt(1)
	v_mfma_f32_32x32x16_bf16 v[50:65], v[96:99], v[112:115], v[50:65]
	ds_read_b128 v[96:99], v154 offset:23104
	ds_read_b128 v[120:123], v154 offset:23136
	s_waitcnt lgkmcnt(1)
	v_mfma_f32_32x32x16_bf16 v[2:17], v[96:99], v[100:103], v[2:17]
	v_mfma_f32_32x32x16_bf16 v[34:49], v[96:99], v[112:115], v[34:49]
	global_load_dwordx4 v[96:99], v[88:89], off offset:128
	global_load_dwordx4 v[100:103], v[80:81], off offset:128
	v_mfma_f32_32x32x16_bf16 v[18:33], v[108:111], v[104:107], v[18:33]
	v_mfma_f32_32x32x16_bf16 v[50:65], v[108:111], v[116:119], v[50:65]
	global_load_dwordx4 v[108:111], v[90:91], off offset:128
	global_load_dwordx4 v[112:115], v[86:87], off offset:128
	global_load_dwordx4 v[124:127], v[66:67], off offset:128
	global_load_dwordx4 v[128:131], v[152:153], off offset:128
	global_load_dwordx4 v[132:135], v[70:71], off offset:128
	global_load_dwordx4 v[136:139], v[68:69], off offset:128
	global_load_dwordx4 v[140:143], v[74:75], off offset:128
	global_load_dwordx4 v[144:147], v[72:73], off offset:128
	s_waitcnt lgkmcnt(0)
	v_mfma_f32_32x32x16_bf16 v[2:17], v[120:123], v[104:107], v[2:17]
	global_load_dwordx4 v[104:107], v[82:83], off offset:128
	global_load_dwordx4 v[148:151], v[84:85], off offset:128
	s_setprio 0
	s_barrier
	s_waitcnt vmcnt(10)
	ds_write_b128 v78, v[100:103]
	ds_write_b128 v78, v[96:99] offset:4608
	s_waitcnt vmcnt(8)
	ds_write_b128 v78, v[112:115] offset:9216
	ds_write_b128 v78, v[108:111] offset:13824
	s_waitcnt vmcnt(6)
	ds_write_b128 v78, v[128:131] offset:18432
	ds_write_b128 v78, v[124:127] offset:23040
	s_waitcnt vmcnt(4)
	ds_write_b128 v78, v[136:139] offset:27648
	ds_write_b128 v78, v[132:135] offset:32256
	s_waitcnt vmcnt(2)
	ds_write_b128 v78, v[144:147] offset:36864
	ds_write_b128 v78, v[140:143] offset:41472
	s_waitcnt vmcnt(1)
	ds_write_b128 v78, v[104:107] offset:46080
	s_waitcnt vmcnt(0)
	ds_write_b128 v78, v[148:151] offset:50688
	v_mfma_f32_32x32x16_bf16 v[34:49], v[120:123], v[116:119], v[34:49]
	s_waitcnt lgkmcnt(0)
	s_setprio 0
	s_barrier
	ds_read_b128 v[96:99], v154 offset:18432
	ds_read_b128 v[100:103], v76
	ds_read_b128 v[104:107], v76 offset:32
	ds_read_b128 v[108:111], v154 offset:18464
	ds_read_b128 v[112:115], v76 offset:4608
	ds_read_b128 v[116:119], v76 offset:4640
	s_waitcnt lgkmcnt(4)
	v_mfma_f32_32x32x16_bf16 v[18:33], v[96:99], v[100:103], v[18:33]
	s_waitcnt lgkmcnt(1)
	v_mfma_f32_32x32x16_bf16 v[50:65], v[96:99], v[112:115], v[50:65]
	ds_read_b128 v[96:99], v154 offset:23040
	ds_read_b128 v[120:123], v154 offset:23072
	s_waitcnt lgkmcnt(1)
	v_mfma_f32_32x32x16_bf16 v[2:17], v[96:99], v[100:103], v[2:17]
	v_mfma_f32_32x32x16_bf16 v[34:49], v[96:99], v[112:115], v[34:49]
	v_mfma_f32_32x32x16_bf16 v[18:33], v[108:111], v[104:107], v[18:33]
	v_mfma_f32_32x32x16_bf16 v[50:65], v[108:111], v[116:119], v[50:65]
	s_waitcnt lgkmcnt(0)
	v_mfma_f32_32x32x16_bf16 v[2:17], v[120:123], v[104:107], v[2:17]
	ds_read_b128 v[96:99], v154 offset:18496
	ds_read_b128 v[100:103], v76 offset:64
	ds_read_b128 v[104:107], v76 offset:96
	ds_read_b128 v[108:111], v154 offset:18528
	v_mfma_f32_32x32x16_bf16 v[34:49], v[120:123], v[116:119], v[34:49]
	ds_read_b128 v[112:115], v76 offset:4672
	ds_read_b128 v[116:119], v76 offset:4704
	s_waitcnt lgkmcnt(4)
	v_mfma_f32_32x32x16_bf16 v[18:33], v[96:99], v[100:103], v[18:33]
	s_waitcnt lgkmcnt(1)
	v_mfma_f32_32x32x16_bf16 v[50:65], v[96:99], v[112:115], v[50:65]
	ds_read_b128 v[96:99], v154 offset:23104
	ds_read_b128 v[120:123], v154 offset:23136
	s_waitcnt lgkmcnt(1)
	v_mfma_f32_32x32x16_bf16 v[2:17], v[96:99], v[100:103], v[2:17]
	v_mfma_f32_32x32x16_bf16 v[34:49], v[96:99], v[112:115], v[34:49]
	global_load_dwordx4 v[96:99], v[88:89], off offset:256
	global_load_dwordx4 v[100:103], v[80:81], off offset:256
	v_mfma_f32_32x32x16_bf16 v[18:33], v[108:111], v[104:107], v[18:33]
	v_mfma_f32_32x32x16_bf16 v[50:65], v[108:111], v[116:119], v[50:65]
	global_load_dwordx4 v[108:111], v[90:91], off offset:256
	global_load_dwordx4 v[112:115], v[86:87], off offset:256
	global_load_dwordx4 v[124:127], v[66:67], off offset:256
	global_load_dwordx4 v[128:131], v[152:153], off offset:256
	global_load_dwordx4 v[132:135], v[70:71], off offset:256
	global_load_dwordx4 v[136:139], v[68:69], off offset:256
	global_load_dwordx4 v[140:143], v[74:75], off offset:256
	global_load_dwordx4 v[144:147], v[72:73], off offset:256
	s_waitcnt lgkmcnt(0)
	v_mfma_f32_32x32x16_bf16 v[2:17], v[120:123], v[104:107], v[2:17]
	global_load_dwordx4 v[104:107], v[82:83], off offset:256
	global_load_dwordx4 v[148:151], v[84:85], off offset:256
	s_setprio 0
	s_barrier
	s_waitcnt vmcnt(10)
	ds_write_b128 v78, v[100:103]
	ds_write_b128 v78, v[96:99] offset:4608
	s_waitcnt vmcnt(8)
	ds_write_b128 v78, v[112:115] offset:9216
	ds_write_b128 v78, v[108:111] offset:13824
	s_waitcnt vmcnt(6)
	ds_write_b128 v78, v[128:131] offset:18432
	ds_write_b128 v78, v[124:127] offset:23040
	s_waitcnt vmcnt(4)
	ds_write_b128 v78, v[136:139] offset:27648
	ds_write_b128 v78, v[132:135] offset:32256
	s_waitcnt vmcnt(2)
	ds_write_b128 v78, v[144:147] offset:36864
	ds_write_b128 v78, v[140:143] offset:41472
	s_waitcnt vmcnt(1)
	ds_write_b128 v78, v[104:107] offset:46080
	s_waitcnt vmcnt(0)
	ds_write_b128 v78, v[148:151] offset:50688
	v_mfma_f32_32x32x16_bf16 v[34:49], v[120:123], v[116:119], v[34:49]
	s_waitcnt lgkmcnt(0)
	s_setprio 0
	s_barrier
	ds_read_b128 v[96:99], v154 offset:18432
	ds_read_b128 v[100:103], v76
	ds_read_b128 v[104:107], v76 offset:32
	ds_read_b128 v[108:111], v154 offset:18464
	ds_read_b128 v[112:115], v76 offset:4608
	ds_read_b128 v[116:119], v76 offset:4640
	s_waitcnt lgkmcnt(4)
	v_mfma_f32_32x32x16_bf16 v[18:33], v[96:99], v[100:103], v[18:33]
	s_waitcnt lgkmcnt(1)
	v_mfma_f32_32x32x16_bf16 v[50:65], v[96:99], v[112:115], v[50:65]
	ds_read_b128 v[96:99], v154 offset:23040
	ds_read_b128 v[120:123], v154 offset:23072
	s_waitcnt lgkmcnt(1)
	v_mfma_f32_32x32x16_bf16 v[2:17], v[96:99], v[100:103], v[2:17]
	v_mfma_f32_32x32x16_bf16 v[34:49], v[96:99], v[112:115], v[34:49]
	v_mfma_f32_32x32x16_bf16 v[18:33], v[108:111], v[104:107], v[18:33]
	v_mfma_f32_32x32x16_bf16 v[50:65], v[108:111], v[116:119], v[50:65]
	s_waitcnt lgkmcnt(0)
	v_mfma_f32_32x32x16_bf16 v[2:17], v[120:123], v[104:107], v[2:17]
	ds_read_b128 v[96:99], v154 offset:18496
	ds_read_b128 v[100:103], v76 offset:64
	ds_read_b128 v[104:107], v76 offset:96
	ds_read_b128 v[108:111], v154 offset:18528
	v_mfma_f32_32x32x16_bf16 v[34:49], v[120:123], v[116:119], v[34:49]
	ds_read_b128 v[112:115], v76 offset:4672
	ds_read_b128 v[116:119], v76 offset:4704
	s_waitcnt lgkmcnt(4)
	v_mfma_f32_32x32x16_bf16 v[18:33], v[96:99], v[100:103], v[18:33]
	s_waitcnt lgkmcnt(1)
	v_mfma_f32_32x32x16_bf16 v[50:65], v[96:99], v[112:115], v[50:65]
	ds_read_b128 v[96:99], v154 offset:23104
	ds_read_b128 v[120:123], v154 offset:23136
	s_waitcnt lgkmcnt(1)
	v_mfma_f32_32x32x16_bf16 v[2:17], v[96:99], v[100:103], v[2:17]
	v_mfma_f32_32x32x16_bf16 v[34:49], v[96:99], v[112:115], v[34:49]
	global_load_dwordx4 v[96:99], v[88:89], off offset:384
	global_load_dwordx4 v[100:103], v[80:81], off offset:384
	v_mfma_f32_32x32x16_bf16 v[18:33], v[108:111], v[104:107], v[18:33]
	v_mfma_f32_32x32x16_bf16 v[50:65], v[108:111], v[116:119], v[50:65]
	global_load_dwordx4 v[88:91], v[90:91], off offset:384
	s_nop 0
	global_load_dwordx4 v[108:111], v[86:87], off offset:384
	global_load_dwordx4 v[112:115], v[66:67], off offset:384
	global_load_dwordx4 v[124:127], v[152:153], off offset:384
	global_load_dwordx4 v[128:131], v[70:71], off offset:384
	s_nop 0
	global_load_dwordx4 v[66:69], v[68:69], off offset:384
	s_nop 0
	global_load_dwordx4 v[132:135], v[74:75], off offset:384
	s_nop 0
	global_load_dwordx4 v[70:73], v[72:73], off offset:384
	s_nop 0
	global_load_dwordx4 v[80:83], v[82:83], off offset:384
	s_nop 0
	global_load_dwordx4 v[84:87], v[84:85], off offset:384
	s_waitcnt lgkmcnt(0)
	s_setprio 0
	s_barrier
	s_waitcnt vmcnt(10)
	ds_write_b128 v78, v[100:103]
	ds_write_b128 v78, v[96:99] offset:4608
	s_waitcnt vmcnt(8)
	ds_write_b128 v78, v[108:111] offset:9216
	ds_write_b128 v78, v[88:91] offset:13824
	s_waitcnt vmcnt(6)
	ds_write_b128 v78, v[124:127] offset:18432
	ds_write_b128 v78, v[112:115] offset:23040
	s_waitcnt vmcnt(4)
	ds_write_b128 v78, v[66:69] offset:27648
	ds_write_b128 v78, v[128:131] offset:32256
	s_waitcnt vmcnt(2)
	ds_write_b128 v78, v[70:73] offset:36864
	ds_write_b128 v78, v[132:135] offset:41472
	s_waitcnt vmcnt(1)
	ds_write_b128 v78, v[80:83] offset:46080
	s_waitcnt vmcnt(0)
	ds_write_b128 v78, v[84:87] offset:50688
	v_mfma_f32_32x32x16_bf16 v[2:17], v[120:123], v[104:107], v[2:17]
	s_waitcnt lgkmcnt(0)
	s_setprio 0
	s_barrier
	ds_read_b128 v[66:69], v154 offset:18432
	ds_read_b128 v[70:73], v76
	ds_read_b128 v[80:83], v76 offset:32
	ds_read_b128 v[84:87], v154 offset:18464
	ds_read_b128 v[88:91], v76 offset:4608
	ds_read_b128 v[96:99], v76 offset:4640
	v_mfma_f32_32x32x16_bf16 v[34:49], v[120:123], v[116:119], v[34:49]
	s_waitcnt lgkmcnt(4)
	v_mfma_f32_32x32x16_bf16 v[18:33], v[66:69], v[70:73], v[18:33]
	s_waitcnt lgkmcnt(1)
	v_mfma_f32_32x32x16_bf16 v[50:65], v[66:69], v[88:91], v[50:65]
	ds_read_b128 v[66:69], v154 offset:23040
	ds_read_b128 v[100:103], v154 offset:23072
	s_waitcnt lgkmcnt(1)
	v_mfma_f32_32x32x16_bf16 v[2:17], v[66:69], v[70:73], v[2:17]
	v_mfma_f32_32x32x16_bf16 v[34:49], v[66:69], v[88:91], v[34:49]
	v_mfma_f32_32x32x16_bf16 v[18:33], v[84:87], v[80:83], v[18:33]
	v_mfma_f32_32x32x16_bf16 v[50:65], v[84:87], v[96:99], v[50:65]
	s_waitcnt lgkmcnt(0)
	v_mfma_f32_32x32x16_bf16 v[2:17], v[100:103], v[80:83], v[2:17]
	ds_read_b128 v[66:69], v154 offset:18496
	ds_read_b128 v[70:73], v76 offset:64
	ds_read_b128 v[80:83], v76 offset:96
	ds_read_b128 v[84:87], v154 offset:18528
	ds_read_b128 v[88:91], v76 offset:4672
	ds_read_b128 v[74:77], v76 offset:4704
	v_mfma_f32_32x32x16_bf16 v[34:49], v[100:103], v[96:99], v[34:49]
	s_waitcnt lgkmcnt(4)
	v_mfma_f32_32x32x16_bf16 v[18:33], v[66:69], v[70:73], v[18:33]
	s_waitcnt lgkmcnt(1)
	v_mfma_f32_32x32x16_bf16 v[50:65], v[66:69], v[88:91], v[50:65]
	ds_read_b128 v[66:69], v154 offset:23104
	ds_read_b128 v[96:99], v154 offset:23136
	s_waitcnt lgkmcnt(0)
	s_setprio 0
	s_barrier
	v_mfma_f32_32x32x16_bf16 v[2:17], v[66:69], v[70:73], v[2:17]
	v_mfma_f32_32x32x16_bf16 v[34:49], v[66:69], v[88:91], v[34:49]
	v_mfma_f32_32x32x16_bf16 v[18:33], v[84:87], v[80:83], v[18:33]
	v_mfma_f32_32x32x16_bf16 v[50:65], v[84:87], v[74:77], v[50:65]
	v_mfma_f32_32x32x16_bf16 v[2:17], v[96:99], v[80:83], v[2:17]
	v_mfma_f32_32x32x16_bf16 v[34:49], v[96:99], v[74:77], v[34:49]
	s_and_saveexec_b64 s[2:3], vcc
	s_cbranch_execz .LBB0_821
	v_bfe_u32 v71, v93, 3, 3
	s_movk_i32 s5, 0x2400
	v_and_b32_e32 v70, 63, v93
	v_and_b32_e32 v67, 4, v71
	v_mul_lo_u32 v72, v94, s5
	v_and_b32_e32 v73, 64, v79
	v_add_u32_e32 v66, s4, v0
	s_cmp_gt_u32 s56, 15
	s_mov_b64 s[18:19], -1
	s_cbranch_scc0 .LBB0_817
	v_mul_u32_u24_e32 v68, 0x90, v67
	v_lshlrev_b32_e32 v69, 1, v92
	v_add3_u32 v74, v72, v68, v69
	v_ashrrev_i32_e32 v68, 7, v66
	s_movk_i32 s4, 0x5f
	v_ashrrev_i32_e32 v69, 31, v68
	v_bitop3_b32 v0, v0, s4, v70 bitop3:0xc8
	v_lshlrev_b64 v[68:69], 14, v[68:69]
	v_cmp_eq_u32_e32 vcc, s4, v0
	v_lshl_add_u64 v[68:69], s[34:35], 0, v[68:69]
	v_lshlrev_b32_e32 v0, 1, v73
	v_lshl_add_u64 v[68:69], v[68:69], 0, v[0:1]
	v_cvt_pk_bf16_f32 v0, v18, s0
	ds_write_b16 v74, v0
	v_cvt_pk_bf16_f32 v0, v19, s0
	ds_write_b16 v74, v0 offset:144
	v_cvt_pk_bf16_f32 v0, v20, s0
	ds_write_b16 v74, v0 offset:288
	v_cvt_pk_bf16_f32 v0, v21, s0
	ds_write_b16 v74, v0 offset:432
	v_cvt_pk_bf16_f32 v0, v22, s0
	ds_write_b16 v74, v0 offset:1152
	v_cvt_pk_bf16_f32 v0, v23, s0
	ds_write_b16 v74, v0 offset:1296
	v_cvt_pk_bf16_f32 v0, v24, s0
	ds_write_b16 v74, v0 offset:1440
	v_cvt_pk_bf16_f32 v0, v25, s0
	ds_write_b16 v74, v0 offset:1584
	v_cvt_pk_bf16_f32 v0, v26, s0
	ds_write_b16 v74, v0 offset:2304
	v_cvt_pk_bf16_f32 v0, v27, s0
	ds_write_b16 v74, v0 offset:2448
	v_cvt_pk_bf16_f32 v0, v28, s0
	ds_write_b16 v74, v0 offset:2592
	v_cvt_pk_bf16_f32 v0, v29, s0
	ds_write_b16 v74, v0 offset:2736
	v_cvt_pk_bf16_f32 v0, v30, s0
	ds_write_b16 v74, v0 offset:3456
	v_cvt_pk_bf16_f32 v0, v31, s0
	ds_write_b16 v74, v0 offset:3600
	v_cvt_pk_bf16_f32 v0, v32, s0
	ds_write_b16 v74, v0 offset:3744
	v_cvt_pk_bf16_f32 v0, v33, s0
	ds_write_b16 v74, v0 offset:3888
	v_cvt_pk_bf16_f32 v0, v2, s0
	ds_write_b16 v74, v0 offset:4608
	v_cvt_pk_bf16_f32 v0, v3, s0
	ds_write_b16 v74, v0 offset:4752
	v_cvt_pk_bf16_f32 v0, v4, s0
	ds_write_b16 v74, v0 offset:4896
	v_cvt_pk_bf16_f32 v0, v5, s0
	ds_write_b16 v74, v0 offset:5040
	v_cvt_pk_bf16_f32 v0, v6, s0
	ds_write_b16 v74, v0 offset:5760
	v_cvt_pk_bf16_f32 v0, v7, s0
	ds_write_b16 v74, v0 offset:5904
	v_cvt_pk_bf16_f32 v0, v8, s0
	ds_write_b16 v74, v0 offset:6048
	v_cvt_pk_bf16_f32 v0, v9, s0
	ds_write_b16 v74, v0 offset:6192
	v_cvt_pk_bf16_f32 v0, v10, s0
	ds_write_b16 v74, v0 offset:6912
	v_cvt_pk_bf16_f32 v0, v11, s0
	ds_write_b16 v74, v0 offset:7056
	v_cvt_pk_bf16_f32 v0, v12, s0
	ds_write_b16 v74, v0 offset:7200
	v_cvt_pk_bf16_f32 v0, v13, s0
	ds_write_b16 v74, v0 offset:7344
	v_cvt_pk_bf16_f32 v0, v14, s0
	ds_write_b16 v74, v0 offset:8064
	v_cvt_pk_bf16_f32 v0, v15, s0
	ds_write_b16 v74, v0 offset:8208
	v_cvt_pk_bf16_f32 v0, v16, s0
	ds_write_b16 v74, v0 offset:8352
	v_cvt_pk_bf16_f32 v0, v17, s0
	ds_write_b16 v74, v0 offset:8496
	v_cvt_pk_bf16_f32 v0, v50, s0
	v_cndmask_b32_e64 v0, v0, 0, vcc
	ds_write_b16 v74, v0 offset:64
	v_cvt_pk_bf16_f32 v0, v51, s0
	v_cndmask_b32_e64 v0, v0, 0, vcc
	ds_write_b16 v74, v0 offset:208
	v_cvt_pk_bf16_f32 v0, v52, s0
	v_cndmask_b32_e64 v0, v0, 0, vcc
	ds_write_b16 v74, v0 offset:352
	v_cvt_pk_bf16_f32 v0, v53, s0
	v_cndmask_b32_e64 v0, v0, 0, vcc
	ds_write_b16 v74, v0 offset:496
	v_cvt_pk_bf16_f32 v0, v54, s0
	v_cndmask_b32_e64 v0, v0, 0, vcc
	ds_write_b16 v74, v0 offset:1216
	v_cvt_pk_bf16_f32 v0, v55, s0
	v_cndmask_b32_e64 v0, v0, 0, vcc
	ds_write_b16 v74, v0 offset:1360
	v_cvt_pk_bf16_f32 v0, v56, s0
	v_cndmask_b32_e64 v0, v0, 0, vcc
	ds_write_b16 v74, v0 offset:1504
	v_cvt_pk_bf16_f32 v0, v57, s0
	v_cndmask_b32_e64 v0, v0, 0, vcc
	ds_write_b16 v74, v0 offset:1648
	v_cvt_pk_bf16_f32 v0, v58, s0
	v_cndmask_b32_e64 v0, v0, 0, vcc
	ds_write_b16 v74, v0 offset:2368
	v_cvt_pk_bf16_f32 v0, v59, s0
	v_cndmask_b32_e64 v0, v0, 0, vcc
	ds_write_b16 v74, v0 offset:2512
	v_cvt_pk_bf16_f32 v0, v60, s0
	v_cndmask_b32_e64 v0, v0, 0, vcc
	ds_write_b16 v74, v0 offset:2656
	v_cvt_pk_bf16_f32 v0, v61, s0
	v_cndmask_b32_e64 v0, v0, 0, vcc
	ds_write_b16 v74, v0 offset:2800
	v_cvt_pk_bf16_f32 v0, v62, s0
	v_cndmask_b32_e64 v0, v0, 0, vcc
	ds_write_b16 v74, v0 offset:3520
	v_cvt_pk_bf16_f32 v0, v63, s0
	v_cndmask_b32_e64 v0, v0, 0, vcc
	ds_write_b16 v74, v0 offset:3664
	v_cvt_pk_bf16_f32 v0, v64, s0
	v_cndmask_b32_e64 v0, v0, 0, vcc
	ds_write_b16 v74, v0 offset:3808
	v_cvt_pk_bf16_f32 v0, v65, s0
	v_cndmask_b32_e64 v0, v0, 0, vcc
	ds_write_b16 v74, v0 offset:3952
	v_cvt_pk_bf16_f32 v0, v34, s0
	v_cndmask_b32_e64 v0, v0, 0, vcc
	ds_write_b16 v74, v0 offset:4672
	v_cvt_pk_bf16_f32 v0, v35, s0
	v_cndmask_b32_e64 v0, v0, 0, vcc
	ds_write_b16 v74, v0 offset:4816
	v_cvt_pk_bf16_f32 v0, v36, s0
	v_cndmask_b32_e64 v0, v0, 0, vcc
	ds_write_b16 v74, v0 offset:4960
	v_cvt_pk_bf16_f32 v0, v37, s0
	v_cndmask_b32_e64 v0, v0, 0, vcc
	ds_write_b16 v74, v0 offset:5104
	v_cvt_pk_bf16_f32 v0, v38, s0
	v_cndmask_b32_e64 v0, v0, 0, vcc
	ds_write_b16 v74, v0 offset:5824
	v_cvt_pk_bf16_f32 v0, v39, s0
	v_cndmask_b32_e64 v0, v0, 0, vcc
	ds_write_b16 v74, v0 offset:5968
	v_cvt_pk_bf16_f32 v0, v40, s0
	v_cndmask_b32_e64 v0, v0, 0, vcc
	ds_write_b16 v74, v0 offset:6112
	v_cvt_pk_bf16_f32 v0, v41, s0
	v_cndmask_b32_e64 v0, v0, 0, vcc
	ds_write_b16 v74, v0 offset:6256
	v_cvt_pk_bf16_f32 v0, v42, s0
	v_cndmask_b32_e64 v0, v0, 0, vcc
	ds_write_b16 v74, v0 offset:6976
	v_cvt_pk_bf16_f32 v0, v43, s0
	v_cndmask_b32_e64 v0, v0, 0, vcc
	ds_write_b16 v74, v0 offset:7120
	v_cvt_pk_bf16_f32 v0, v44, s0
	v_cndmask_b32_e64 v0, v0, 0, vcc
	ds_write_b16 v74, v0 offset:7264
	v_cvt_pk_bf16_f32 v0, v45, s0
	v_cndmask_b32_e64 v0, v0, 0, vcc
	ds_write_b16 v74, v0 offset:7408
	v_cvt_pk_bf16_f32 v0, v46, s0
	v_cndmask_b32_e64 v0, v0, 0, vcc
	ds_write_b16 v74, v0 offset:8128
	v_cvt_pk_bf16_f32 v0, v47, s0
	v_cndmask_b32_e64 v0, v0, 0, vcc
	ds_write_b16 v74, v0 offset:8272
	v_cvt_pk_bf16_f32 v0, v48, s0
	v_cndmask_b32_e64 v0, v0, 0, vcc
	ds_write_b16 v74, v0 offset:8416
	v_cvt_pk_bf16_f32 v0, v49, s0
	v_cndmask_b32_e64 v0, v0, 0, vcc
	ds_write_b16 v74, v0 offset:8560
	v_lshlrev_b32_e32 v0, 8, v71
	v_lshl_add_u64 v[68:69], v[68:69], 0, v[0:1]
	s_mov_b64 s[4:5], 0xd080000
	v_lshl_add_u64 v[68:69], v[68:69], 0, s[4:5]
	s_mov_b64 s[18:19], 0
